# P0 rmsnorm row loop rewritten by hand (gains hoisted, 8 loads per row in flight, next row prefetched); rowscale loads hoisted in GEMM epilogues; mode-3 epilogue as before
# speedup vs baseline: 1.0132x; 1.0132x over previous
;     __device__ __forceinline__ void operator()(const f32x4 (&acc)[2][2][4][2], const Unit& u, int wr, int wc, int fr, int fq) const {
;     ...
;         const bool rowscale = (rs != nullptr) && (mode != 4);
;         const bool act = (mode == 1) && (u.pn < 8), stat = (mode == 1) && (u.pn >= 4) && (u.pn < 12);
;         float* ssp = ss_out + (u.pn < 8 ? 0 : (u.pn < 10 ? 32768 : 65536));
;         const int col0 = (mode == 2 ? u.pn * HALF : u.pn * BM) + wc * 32 + 8 * fq;
; #pragma unroll
;         for (int ai = 0; ai < 2; ++ai)
; #pragma unroll
;             for (int m = 0; m < 4; ++m) { const int row = row0 + ai * HALF + m * 16; bf16_t* rowp = O + (size_t)row * ldc + col0;
;                 float r = 1.0f; if (rowscale) r = __builtin_amdgcn_rsqf(rs[row] * rs_invn + 1e-6f);
.LBB0_94:
	v_cndmask_b32_e64 v136, 0, 1, s[70:71]
	v_cmp_ne_u32_e64 s[44:45], 1, v136
	s_andn2_b64 vcc, exec, s[70:71]
	v_lshl_add_u64 v[136:137], v[156:157], 2, s[92:93]
	s_cbranch_vccnz .LBB0_96
	global_load_dword v240, v[136:137], off
	global_load_dword v241, v[136:137], off offset:64
	global_load_dword v242, v[136:137], off offset:128
	global_load_dword v243, v[136:137], off offset:192
	global_load_dword v244, v[136:137], off offset:512
	global_load_dword v245, v[136:137], off offset:576
	global_load_dword v246, v[136:137], off offset:640
	global_load_dword v247, v[136:137], off offset:704
	s_waitcnt vmcnt(0)
	v_fma_f32 v138, s9, v240, v214
	v_rsq_f32_e32 v162, v138
	s_branch .LBB0_97

;     __device__ __forceinline__ void operator()(const f32x4 (&acc)[2][2][4][2], const Unit& u, int wr, int wc, int fr, int fq) const {
;     ...
;             for (int m = 0; m < 4; ++m) { const int row = row0 + ai * HALF + m * 16; bf16_t* rowp = O + (size_t)row * ldc + col0;
;                 float r = 1.0f; if (rowscale) r = __builtin_amdgcn_rsqf(rs[row] * rs_invn + 1e-6f);
.LBB0_100:
	v_fma_f32 v140, s9, v241, v214
	v_rsq_f32_e32 v164, v140
	s_branch .LBB0_112

;     __device__ __forceinline__ void operator()(const f32x4 (&acc)[2][2][4][2], const Unit& u, int wr, int wc, int fr, int fq) const {
;     ...
;             for (int m = 0; m < 4; ++m) { const int row = row0 + ai * HALF + m * 16; bf16_t* rowp = O + (size_t)row * ldc + col0;
;                 float r = 1.0f; if (rowscale) r = __builtin_amdgcn_rsqf(rs[row] * rs_invn + 1e-6f);
.LBB0_115:
	v_fma_f32 v140, s9, v242, v214
	v_rsq_f32_e32 v164, v140
	s_branch .LBB0_127

;     __device__ __forceinline__ void operator()(const f32x4 (&acc)[2][2][4][2], const Unit& u, int wr, int wc, int fr, int fq) const {
;     ...
;             for (int m = 0; m < 4; ++m) { const int row = row0 + ai * HALF + m * 16; bf16_t* rowp = O + (size_t)row * ldc + col0;
;                 float r = 1.0f; if (rowscale) r = __builtin_amdgcn_rsqf(rs[row] * rs_invn + 1e-6f);
.LBB0_130:
	v_fma_f32 v140, s9, v243, v214
	v_rsq_f32_e32 v164, v140
	s_branch .LBB0_142

;     __device__ __forceinline__ void operator()(const f32x4 (&acc)[2][2][4][2], const Unit& u, int wr, int wc, int fr, int fq) const {
;     ...
;             for (int m = 0; m < 4; ++m) { const int row = row0 + ai * HALF + m * 16; bf16_t* rowp = O + (size_t)row * ldc + col0;
;                 float r = 1.0f; if (rowscale) r = __builtin_amdgcn_rsqf(rs[row] * rs_invn + 1e-6f);
.LBB0_145:
	v_fma_f32 v140, s9, v244, v214
	v_rsq_f32_e32 v164, v140
	s_branch .LBB0_157

;     __device__ __forceinline__ void operator()(const f32x4 (&acc)[2][2][4][2], const Unit& u, int wr, int wc, int fr, int fq) const {
;     ...
;             for (int m = 0; m < 4; ++m) { const int row = row0 + ai * HALF + m * 16; bf16_t* rowp = O + (size_t)row * ldc + col0;
;                 float r = 1.0f; if (rowscale) r = __builtin_amdgcn_rsqf(rs[row] * rs_invn + 1e-6f);
.LBB0_160:
	v_fma_f32 v140, s9, v245, v214
	v_rsq_f32_e32 v164, v140
	s_branch .LBB0_172

;     __device__ __forceinline__ void operator()(const f32x4 (&acc)[2][2][4][2], const Unit& u, int wr, int wc, int fr, int fq) const {
;     ...
;             for (int m = 0; m < 4; ++m) { const int row = row0 + ai * HALF + m * 16; bf16_t* rowp = O + (size_t)row * ldc + col0;
;                 float r = 1.0f; if (rowscale) r = __builtin_amdgcn_rsqf(rs[row] * rs_invn + 1e-6f);
.LBB0_175:
	v_fma_f32 v140, s9, v246, v214
	v_rsq_f32_e32 v164, v140
	s_branch .LBB0_187

;     __device__ __forceinline__ void operator()(const f32x4 (&acc)[2][2][4][2], const Unit& u, int wr, int wc, int fr, int fq) const {
;     ...
;             for (int m = 0; m < 4; ++m) { const int row = row0 + ai * HALF + m * 16; bf16_t* rowp = O + (size_t)row * ldc + col0;
;                 float r = 1.0f; if (rowscale) r = __builtin_amdgcn_rsqf(rs[row] * rs_invn + 1e-6f);
.LBB0_190:
	v_fma_f32 v136, s9, v247, v214
	v_rsq_f32_e32 v160, v136
	s_branch .LBB0_202

; __device__ __forceinline__ unsigned cvt_pk_bf16(float lo, float hi) { f32x2 v = {lo, hi}; bf16x2_t b = __builtin_convertvector(v, bf16x2_t); return __builtin_bit_cast(unsigned, b); }
; #define KIN(i) (*(const float* const __attribute__((address_space(4)))*)(kp + 8 * (i)))
; __device__ __forceinline__ void rms_row_to_bf16(const float* xrow, const float* g, bf16* orow, int lane) {
;     const f32x4* xr = (const f32x4*)xrow + lane; const f32x4* gr = (const f32x4*)g + lane;
;     f32x4 v[8]; float s = 0.f;
; #pragma unroll
;     for (int j = 0; j < 8; ++j) { v[j] = xr[64 * j]; s += (v[j].x * v[j].x + v[j].y * v[j].y) + (v[j].z * v[j].z + v[j].w * v[j].w); }
;     const float r = 1.0f / sqrtf(wave_sum(s) * (1.0f / DM) + EPS);
;     u32x2* o8 = (u32x2*)orow + lane;
; #pragma unroll
;     for (int j = 0; j < 8; ++j) { const f32x4 gg = gr[64 * j]; u32x2 w; w.x = cvt_pk_bf16(v[j].x * r * gg.x, v[j].y * r * gg.y); w.y = cvt_pk_bf16(v[j].z * r * gg.z, v[j].w * r * gg.w); o8[64 * j] = w; }
; }
; __global__ void __launch_bounds__(512, 2) fwd_megakernel(Args a) {
;     ...
;             for (int m = gw; m < MTOK; m += NGW) rms_row_to_bf16(KIN(0) + (size_t)m * DM, KIN(2), XN + (size_t)m * DM, lane);
.LBB0_503:
	global_load_dwordx4 v[64:67], v[38:39], off
	global_load_dwordx4 v[68:71], v[38:39], off offset:1024
	global_load_dwordx4 v[72:75], v[38:39], off offset:2048
	global_load_dwordx4 v[76:79], v[38:39], off offset:3072
	global_load_dwordx4 v[80:83], v[40:41], off
	global_load_dwordx4 v[84:87], v[42:43], off
	global_load_dwordx4 v[88:91], v[44:45], off
	global_load_dwordx4 v[92:95], v[46:47], off
	v_add_co_u32_e32 v2, vcc, 0xfffff000, v50
	s_nop 1
	v_addc_co_u32_e32 v3, vcc, -1, v51, vcc
	global_load_dwordx4 v[116:119], v[2:3], off offset:-3072
	global_load_dwordx4 v[120:123], v[2:3], off offset:-2048
	global_load_dwordx4 v[124:127], v[2:3], off offset:-1024
	global_load_dwordx4 v[128:131], v[2:3], off
	global_load_dwordx4 v[132:135], v[50:51], off offset:-3072
	global_load_dwordx4 v[136:139], v[50:51], off offset:-2048
	global_load_dwordx4 v[140:143], v[50:51], off offset:-1024
	global_load_dwordx4 v[144:147], v[50:51], off
	v_lshl_add_u64 v[50:51], v[50:51], 0, s[86:87]
.Lrms_loop:
	s_add_i32 s88, s88, s66
	s_cmpk_gt_i32 s88, 0x7fff
	s_cbranch_scc1 .Lrms_last_a
	v_add_co_u32_e32 v2, vcc, 0xfffff000, v50
	s_nop 1
	v_addc_co_u32_e32 v3, vcc, -1, v51, vcc
	global_load_dwordx4 v[148:151], v[2:3], off offset:-3072
	global_load_dwordx4 v[152:155], v[2:3], off offset:-2048
	global_load_dwordx4 v[156:159], v[2:3], off offset:-1024
	global_load_dwordx4 v[160:163], v[2:3], off
	global_load_dwordx4 v[164:167], v[50:51], off offset:-3072
	global_load_dwordx4 v[168:171], v[50:51], off offset:-2048
	global_load_dwordx4 v[172:175], v[50:51], off offset:-1024
	global_load_dwordx4 v[176:179], v[50:51], off
	v_lshl_add_u64 v[50:51], v[50:51], 0, s[86:87]
	s_waitcnt vmcnt(8)
	v_pk_mul_f32 v[4:5], v[116:117], v[116:117]
	v_pk_mul_f32 v[6:7], v[118:119], v[118:119]
	v_pk_fma_f32 v[4:5], v[120:121], v[120:121], v[4:5]
	v_pk_fma_f32 v[6:7], v[122:123], v[122:123], v[6:7]
	v_pk_fma_f32 v[4:5], v[124:125], v[124:125], v[4:5]
	v_pk_fma_f32 v[6:7], v[126:127], v[126:127], v[6:7]
	v_pk_fma_f32 v[4:5], v[128:129], v[128:129], v[4:5]
	v_pk_fma_f32 v[6:7], v[130:131], v[130:131], v[6:7]
	v_pk_fma_f32 v[4:5], v[132:133], v[132:133], v[4:5]
	v_pk_fma_f32 v[6:7], v[134:135], v[134:135], v[6:7]
	v_pk_fma_f32 v[4:5], v[136:137], v[136:137], v[4:5]
	v_pk_fma_f32 v[6:7], v[138:139], v[138:139], v[6:7]
	v_pk_fma_f32 v[4:5], v[140:141], v[140:141], v[4:5]
	v_pk_fma_f32 v[6:7], v[142:143], v[142:143], v[6:7]
	v_pk_fma_f32 v[4:5], v[144:145], v[144:145], v[4:5]
	v_pk_fma_f32 v[6:7], v[146:147], v[146:147], v[6:7]
	v_pk_add_f32 v[4:5], v[4:5], v[6:7]
	s_nop 0
	v_add_f32_e32 v34, v4, v5
	ds_bpermute_b32 v35, v1, v34
	s_waitcnt lgkmcnt(0)
	v_add_f32_e32 v34, v34, v35
	ds_bpermute_b32 v35, v53, v34
	s_waitcnt lgkmcnt(0)
	v_add_f32_e32 v34, v34, v35
	ds_bpermute_b32 v35, v54, v34
	s_waitcnt lgkmcnt(0)
	v_add_f32_e32 v34, v34, v35
	ds_bpermute_b32 v35, v55, v34
	s_waitcnt lgkmcnt(0)
	v_add_f32_e32 v34, v34, v35
	ds_bpermute_b32 v35, v56, v34
	s_waitcnt lgkmcnt(0)
	v_add_f32_e32 v34, v34, v35
	ds_bpermute_b32 v35, v57, v34
	s_waitcnt lgkmcnt(0)
	v_add_f32_e32 v34, v34, v35
	v_fmamk_f32 v34, v34, 0x3a000000, v214
	v_cmp_gt_f32_e32 vcc, s33, v34
	v_mul_f32_e32 v35, 0x4f800000, v34
	s_nop 0
	v_cndmask_b32_e32 v34, v34, v35, vcc
	v_sqrt_f32_e32 v35, v34
	s_nop 0
	v_add_u32_e32 v36, -1, v35
	v_fma_f32 v37, -v36, v35, v34
	v_cmp_ge_f32_e64 s[4:5], 0, v37
	v_add_u32_e32 v37, 1, v35
	s_nop 0
	v_cndmask_b32_e64 v36, v35, v36, s[4:5]
	v_fma_f32 v35, -v37, v35, v34
	v_cmp_lt_f32_e64 s[4:5], 0, v35
	s_nop 1
	v_cndmask_b32_e64 v35, v36, v37, s[4:5]
	v_mul_f32_e32 v36, 0x37800000, v35
	v_cndmask_b32_e32 v35, v35, v36, vcc
	v_cmp_class_f32_e32 vcc, v34, v215
	s_nop 1
	v_cndmask_b32_e32 v34, v35, v34, vcc
	v_div_scale_f32 v35, s[4:5], v34, v34, 1.0
	v_rcp_f32_e32 v36, v35
	s_nop 0
	v_fma_f32 v37, -v35, v36, 1.0
	v_fmac_f32_e32 v36, v37, v36
	v_div_scale_f32 v37, vcc, 1.0, v34, 1.0
	v_mul_f32_e32 v52, v37, v36
	v_fma_f32 v58, -v35, v52, v37
	v_fmac_f32_e32 v52, v58, v36
	v_fma_f32 v35, -v35, v52, v37
	v_div_fmas_f32 v35, v35, v36, v52
	v_div_fixup_f32 v52, v35, v34, 1.0
	v_pk_mul_f32 v[2:3], v[116:117], v[52:53] op_sel_hi:[1,0]
	v_pk_mul_f32 v[4:5], v[118:119], v[52:53] op_sel_hi:[1,0]
	v_pk_mul_f32 v[2:3], v[64:65], v[2:3]
	v_pk_mul_f32 v[4:5], v[66:67], v[4:5]
	v_cvt_pk_bf16_f32 v8, v2, v3
	v_cvt_pk_bf16_f32 v9, v4, v5
	global_store_dwordx2 v[48:49], v[8:9], off offset:-3584
	v_pk_mul_f32 v[2:3], v[120:121], v[52:53] op_sel_hi:[1,0]
	v_pk_mul_f32 v[4:5], v[122:123], v[52:53] op_sel_hi:[1,0]
	v_pk_mul_f32 v[2:3], v[68:69], v[2:3]
	v_pk_mul_f32 v[4:5], v[70:71], v[4:5]
	v_cvt_pk_bf16_f32 v10, v2, v3
	v_cvt_pk_bf16_f32 v11, v4, v5
	global_store_dwordx2 v[48:49], v[10:11], off offset:-3072
	v_pk_mul_f32 v[2:3], v[124:125], v[52:53] op_sel_hi:[1,0]
	v_pk_mul_f32 v[4:5], v[126:127], v[52:53] op_sel_hi:[1,0]
	v_pk_mul_f32 v[2:3], v[72:73], v[2:3]
	v_pk_mul_f32 v[4:5], v[74:75], v[4:5]
	v_cvt_pk_bf16_f32 v12, v2, v3
	v_cvt_pk_bf16_f32 v13, v4, v5
	global_store_dwordx2 v[48:49], v[12:13], off offset:-2560
	v_pk_mul_f32 v[2:3], v[128:129], v[52:53] op_sel_hi:[1,0]
	v_pk_mul_f32 v[4:5], v[130:131], v[52:53] op_sel_hi:[1,0]
	v_pk_mul_f32 v[2:3], v[76:77], v[2:3]
	v_pk_mul_f32 v[4:5], v[78:79], v[4:5]
	v_cvt_pk_bf16_f32 v14, v2, v3
	v_cvt_pk_bf16_f32 v15, v4, v5
	global_store_dwordx2 v[48:49], v[14:15], off offset:-2048
	v_pk_mul_f32 v[2:3], v[132:133], v[52:53] op_sel_hi:[1,0]
	v_pk_mul_f32 v[4:5], v[134:135], v[52:53] op_sel_hi:[1,0]
	v_pk_mul_f32 v[2:3], v[80:81], v[2:3]
	v_pk_mul_f32 v[4:5], v[82:83], v[4:5]
	v_cvt_pk_bf16_f32 v16, v2, v3
	v_cvt_pk_bf16_f32 v17, v4, v5
	global_store_dwordx2 v[48:49], v[16:17], off offset:-1536
	v_pk_mul_f32 v[2:3], v[136:137], v[52:53] op_sel_hi:[1,0]
	v_pk_mul_f32 v[4:5], v[138:139], v[52:53] op_sel_hi:[1,0]
	v_pk_mul_f32 v[2:3], v[84:85], v[2:3]
	v_pk_mul_f32 v[4:5], v[86:87], v[4:5]
	v_cvt_pk_bf16_f32 v18, v2, v3
	v_cvt_pk_bf16_f32 v19, v4, v5
	global_store_dwordx2 v[48:49], v[18:19], off offset:-1024
	v_pk_mul_f32 v[2:3], v[140:141], v[52:53] op_sel_hi:[1,0]
	v_pk_mul_f32 v[4:5], v[142:143], v[52:53] op_sel_hi:[1,0]
	v_pk_mul_f32 v[2:3], v[88:89], v[2:3]
	v_pk_mul_f32 v[4:5], v[90:91], v[4:5]
	v_cvt_pk_bf16_f32 v20, v2, v3
	v_cvt_pk_bf16_f32 v21, v4, v5
	global_store_dwordx2 v[48:49], v[20:21], off offset:-512
	v_pk_mul_f32 v[2:3], v[144:145], v[52:53] op_sel_hi:[1,0]
	v_pk_mul_f32 v[4:5], v[146:147], v[52:53] op_sel_hi:[1,0]
	v_pk_mul_f32 v[2:3], v[92:93], v[2:3]
	v_pk_mul_f32 v[4:5], v[94:95], v[4:5]
	v_cvt_pk_bf16_f32 v22, v2, v3
	v_cvt_pk_bf16_f32 v23, v4, v5
	global_store_dwordx2 v[48:49], v[22:23], off
	v_lshl_add_u64 v[48:49], v[48:49], 0, s[6:7]
	s_add_i32 s88, s88, s66
	s_cmpk_gt_i32 s88, 0x7fff
	s_cbranch_scc1 .Lrms_last_b
; __device__ __forceinline__ unsigned cvt_pk_bf16(float lo, float hi) { f32x2 v = {lo, hi}; bf16x2_t b = __builtin_convertvector(v, bf16x2_t); return __builtin_bit_cast(unsigned, b); }
; __device__ __forceinline__ void rms_row_to_bf16(const float* xrow, const float* g, bf16* orow, int lane) {
;     const f32x4* xr = (const f32x4*)xrow + lane; const f32x4* gr = (const f32x4*)g + lane;
;     f32x4 v[8]; float s = 0.f;
; #pragma unroll
;     for (int j = 0; j < 8; ++j) { v[j] = xr[64 * j]; s += (v[j].x * v[j].x + v[j].y * v[j].y) + (v[j].z * v[j].z + v[j].w * v[j].w); }
;     const float r = 1.0f / sqrtf(wave_sum(s) * (1.0f / DM) + EPS);
;     u32x2* o8 = (u32x2*)orow + lane;
; #pragma unroll
;     for (int j = 0; j < 8; ++j) { const f32x4 gg = gr[64 * j]; u32x2 w; w.x = cvt_pk_bf16(v[j].x * r * gg.x, v[j].y * r * gg.y); w.y = cvt_pk_bf16(v[j].z * r * gg.z, v[j].w * r * gg.w); o8[64 * j] = w; }
; }
	v_add_co_u32_e32 v2, vcc, 0xfffff000, v50
	s_nop 1
	v_addc_co_u32_e32 v3, vcc, -1, v51, vcc
	global_load_dwordx4 v[116:119], v[2:3], off offset:-3072
	global_load_dwordx4 v[120:123], v[2:3], off offset:-2048
	global_load_dwordx4 v[124:127], v[2:3], off offset:-1024
	global_load_dwordx4 v[128:131], v[2:3], off
	global_load_dwordx4 v[132:135], v[50:51], off offset:-3072
	global_load_dwordx4 v[136:139], v[50:51], off offset:-2048
	global_load_dwordx4 v[140:143], v[50:51], off offset:-1024
	global_load_dwordx4 v[144:147], v[50:51], off
	v_lshl_add_u64 v[50:51], v[50:51], 0, s[86:87]
	s_waitcnt vmcnt(8)
	v_pk_mul_f32 v[4:5], v[148:149], v[148:149]
	v_pk_mul_f32 v[6:7], v[150:151], v[150:151]
	v_pk_fma_f32 v[4:5], v[152:153], v[152:153], v[4:5]
	v_pk_fma_f32 v[6:7], v[154:155], v[154:155], v[6:7]
	v_pk_fma_f32 v[4:5], v[156:157], v[156:157], v[4:5]
	v_pk_fma_f32 v[6:7], v[158:159], v[158:159], v[6:7]
	v_pk_fma_f32 v[4:5], v[160:161], v[160:161], v[4:5]
	v_pk_fma_f32 v[6:7], v[162:163], v[162:163], v[6:7]
	v_pk_fma_f32 v[4:5], v[164:165], v[164:165], v[4:5]
	v_pk_fma_f32 v[6:7], v[166:167], v[166:167], v[6:7]
	v_pk_fma_f32 v[4:5], v[168:169], v[168:169], v[4:5]
	v_pk_fma_f32 v[6:7], v[170:171], v[170:171], v[6:7]
	v_pk_fma_f32 v[4:5], v[172:173], v[172:173], v[4:5]
	v_pk_fma_f32 v[6:7], v[174:175], v[174:175], v[6:7]
	v_pk_fma_f32 v[4:5], v[176:177], v[176:177], v[4:5]
	v_pk_fma_f32 v[6:7], v[178:179], v[178:179], v[6:7]
	v_pk_add_f32 v[4:5], v[4:5], v[6:7]
	s_nop 0
	v_add_f32_e32 v34, v4, v5
	ds_bpermute_b32 v35, v1, v34
	s_waitcnt lgkmcnt(0)
	v_add_f32_e32 v34, v34, v35
	ds_bpermute_b32 v35, v53, v34
	s_waitcnt lgkmcnt(0)
	v_add_f32_e32 v34, v34, v35
	ds_bpermute_b32 v35, v54, v34
	s_waitcnt lgkmcnt(0)
	v_add_f32_e32 v34, v34, v35
	ds_bpermute_b32 v35, v55, v34
	s_waitcnt lgkmcnt(0)
	v_add_f32_e32 v34, v34, v35
	ds_bpermute_b32 v35, v56, v34
	s_waitcnt lgkmcnt(0)
	v_add_f32_e32 v34, v34, v35
	ds_bpermute_b32 v35, v57, v34
	s_waitcnt lgkmcnt(0)
	v_add_f32_e32 v34, v34, v35
	v_fmamk_f32 v34, v34, 0x3a000000, v214
	v_cmp_gt_f32_e32 vcc, s33, v34
	v_mul_f32_e32 v35, 0x4f800000, v34
	s_nop 0
	v_cndmask_b32_e32 v34, v34, v35, vcc
	v_sqrt_f32_e32 v35, v34
	s_nop 0
	v_add_u32_e32 v36, -1, v35
	v_fma_f32 v37, -v36, v35, v34
	v_cmp_ge_f32_e64 s[4:5], 0, v37
	v_add_u32_e32 v37, 1, v35
	s_nop 0
	v_cndmask_b32_e64 v36, v35, v36, s[4:5]
	v_fma_f32 v35, -v37, v35, v34
	v_cmp_lt_f32_e64 s[4:5], 0, v35
	s_nop 1
	v_cndmask_b32_e64 v35, v36, v37, s[4:5]
	v_mul_f32_e32 v36, 0x37800000, v35
	v_cndmask_b32_e32 v35, v35, v36, vcc
	v_cmp_class_f32_e32 vcc, v34, v215
	s_nop 1
	v_cndmask_b32_e32 v34, v35, v34, vcc
	v_div_scale_f32 v35, s[4:5], v34, v34, 1.0
	v_rcp_f32_e32 v36, v35
	s_nop 0
	v_fma_f32 v37, -v35, v36, 1.0
	v_fmac_f32_e32 v36, v37, v36
	v_div_scale_f32 v37, vcc, 1.0, v34, 1.0
	v_mul_f32_e32 v52, v37, v36
	v_fma_f32 v58, -v35, v52, v37
	v_fmac_f32_e32 v52, v58, v36
	v_fma_f32 v35, -v35, v52, v37
	v_div_fmas_f32 v35, v35, v36, v52
	v_div_fixup_f32 v52, v35, v34, 1.0
	v_pk_mul_f32 v[2:3], v[148:149], v[52:53] op_sel_hi:[1,0]
	v_pk_mul_f32 v[4:5], v[150:151], v[52:53] op_sel_hi:[1,0]
	v_pk_mul_f32 v[2:3], v[64:65], v[2:3]
	v_pk_mul_f32 v[4:5], v[66:67], v[4:5]
	v_cvt_pk_bf16_f32 v8, v2, v3
	v_cvt_pk_bf16_f32 v9, v4, v5
	global_store_dwordx2 v[48:49], v[8:9], off offset:-3584
	v_pk_mul_f32 v[2:3], v[152:153], v[52:53] op_sel_hi:[1,0]
	v_pk_mul_f32 v[4:5], v[154:155], v[52:53] op_sel_hi:[1,0]
	v_pk_mul_f32 v[2:3], v[68:69], v[2:3]
	v_pk_mul_f32 v[4:5], v[70:71], v[4:5]
	v_cvt_pk_bf16_f32 v10, v2, v3
	v_cvt_pk_bf16_f32 v11, v4, v5
	global_store_dwordx2 v[48:49], v[10:11], off offset:-3072
	v_pk_mul_f32 v[2:3], v[156:157], v[52:53] op_sel_hi:[1,0]
	v_pk_mul_f32 v[4:5], v[158:159], v[52:53] op_sel_hi:[1,0]
	v_pk_mul_f32 v[2:3], v[72:73], v[2:3]
	v_pk_mul_f32 v[4:5], v[74:75], v[4:5]
	v_cvt_pk_bf16_f32 v12, v2, v3
	v_cvt_pk_bf16_f32 v13, v4, v5
	global_store_dwordx2 v[48:49], v[12:13], off offset:-2560
	v_pk_mul_f32 v[2:3], v[160:161], v[52:53] op_sel_hi:[1,0]
	v_pk_mul_f32 v[4:5], v[162:163], v[52:53] op_sel_hi:[1,0]
	v_pk_mul_f32 v[2:3], v[76:77], v[2:3]
	v_pk_mul_f32 v[4:5], v[78:79], v[4:5]
	v_cvt_pk_bf16_f32 v14, v2, v3
	v_cvt_pk_bf16_f32 v15, v4, v5
	global_store_dwordx2 v[48:49], v[14:15], off offset:-2048
	v_pk_mul_f32 v[2:3], v[164:165], v[52:53] op_sel_hi:[1,0]
	v_pk_mul_f32 v[4:5], v[166:167], v[52:53] op_sel_hi:[1,0]
	v_pk_mul_f32 v[2:3], v[80:81], v[2:3]
	v_pk_mul_f32 v[4:5], v[82:83], v[4:5]
	v_cvt_pk_bf16_f32 v16, v2, v3
	v_cvt_pk_bf16_f32 v17, v4, v5
	global_store_dwordx2 v[48:49], v[16:17], off offset:-1536
	v_pk_mul_f32 v[2:3], v[168:169], v[52:53] op_sel_hi:[1,0]
	v_pk_mul_f32 v[4:5], v[170:171], v[52:53] op_sel_hi:[1,0]
	v_pk_mul_f32 v[2:3], v[84:85], v[2:3]
	v_pk_mul_f32 v[4:5], v[86:87], v[4:5]
	v_cvt_pk_bf16_f32 v18, v2, v3
	v_cvt_pk_bf16_f32 v19, v4, v5
	global_store_dwordx2 v[48:49], v[18:19], off offset:-1024
	v_pk_mul_f32 v[2:3], v[172:173], v[52:53] op_sel_hi:[1,0]
	v_pk_mul_f32 v[4:5], v[174:175], v[52:53] op_sel_hi:[1,0]
	v_pk_mul_f32 v[2:3], v[88:89], v[2:3]
	v_pk_mul_f32 v[4:5], v[90:91], v[4:5]
	v_cvt_pk_bf16_f32 v20, v2, v3
	v_cvt_pk_bf16_f32 v21, v4, v5
	global_store_dwordx2 v[48:49], v[20:21], off offset:-512
	v_pk_mul_f32 v[2:3], v[176:177], v[52:53] op_sel_hi:[1,0]
	v_pk_mul_f32 v[4:5], v[178:179], v[52:53] op_sel_hi:[1,0]
	v_pk_mul_f32 v[2:3], v[92:93], v[2:3]
	v_pk_mul_f32 v[4:5], v[94:95], v[4:5]
	v_cvt_pk_bf16_f32 v22, v2, v3
	v_cvt_pk_bf16_f32 v23, v4, v5
	global_store_dwordx2 v[48:49], v[22:23], off
	v_lshl_add_u64 v[48:49], v[48:49], 0, s[6:7]
	s_branch .Lrms_loop
; __device__ __forceinline__ unsigned cvt_pk_bf16(float lo, float hi) { f32x2 v = {lo, hi}; bf16x2_t b = __builtin_convertvector(v, bf16x2_t); return __builtin_bit_cast(unsigned, b); }
; __device__ __forceinline__ void rms_row_to_bf16(const float* xrow, const float* g, bf16* orow, int lane) {
;     const f32x4* xr = (const f32x4*)xrow + lane; const f32x4* gr = (const f32x4*)g + lane;
;     f32x4 v[8]; float s = 0.f;
; #pragma unroll
;     for (int j = 0; j < 8; ++j) { v[j] = xr[64 * j]; s += (v[j].x * v[j].x + v[j].y * v[j].y) + (v[j].z * v[j].z + v[j].w * v[j].w); }
;     const float r = 1.0f / sqrtf(wave_sum(s) * (1.0f / DM) + EPS);
;     u32x2* o8 = (u32x2*)orow + lane;
; #pragma unroll
;     for (int j = 0; j < 8; ++j) { const f32x4 gg = gr[64 * j]; u32x2 w; w.x = cvt_pk_bf16(v[j].x * r * gg.x, v[j].y * r * gg.y); w.y = cvt_pk_bf16(v[j].z * r * gg.z, v[j].w * r * gg.w); o8[64 * j] = w; }
; }
.Lrms_last_a:
	s_waitcnt vmcnt(0)
	v_pk_mul_f32 v[4:5], v[116:117], v[116:117]
	v_pk_mul_f32 v[6:7], v[118:119], v[118:119]
	v_pk_fma_f32 v[4:5], v[120:121], v[120:121], v[4:5]
	v_pk_fma_f32 v[6:7], v[122:123], v[122:123], v[6:7]
	v_pk_fma_f32 v[4:5], v[124:125], v[124:125], v[4:5]
	v_pk_fma_f32 v[6:7], v[126:127], v[126:127], v[6:7]
	v_pk_fma_f32 v[4:5], v[128:129], v[128:129], v[4:5]
	v_pk_fma_f32 v[6:7], v[130:131], v[130:131], v[6:7]
	v_pk_fma_f32 v[4:5], v[132:133], v[132:133], v[4:5]
	v_pk_fma_f32 v[6:7], v[134:135], v[134:135], v[6:7]
	v_pk_fma_f32 v[4:5], v[136:137], v[136:137], v[4:5]
	v_pk_fma_f32 v[6:7], v[138:139], v[138:139], v[6:7]
	v_pk_fma_f32 v[4:5], v[140:141], v[140:141], v[4:5]
	v_pk_fma_f32 v[6:7], v[142:143], v[142:143], v[6:7]
	v_pk_fma_f32 v[4:5], v[144:145], v[144:145], v[4:5]
	v_pk_fma_f32 v[6:7], v[146:147], v[146:147], v[6:7]
	v_pk_add_f32 v[4:5], v[4:5], v[6:7]
	s_nop 0
	v_add_f32_e32 v34, v4, v5
	ds_bpermute_b32 v35, v1, v34
	s_waitcnt lgkmcnt(0)
	v_add_f32_e32 v34, v34, v35
	ds_bpermute_b32 v35, v53, v34
	s_waitcnt lgkmcnt(0)
	v_add_f32_e32 v34, v34, v35
	ds_bpermute_b32 v35, v54, v34
	s_waitcnt lgkmcnt(0)
	v_add_f32_e32 v34, v34, v35
	ds_bpermute_b32 v35, v55, v34
	s_waitcnt lgkmcnt(0)
	v_add_f32_e32 v34, v34, v35
	ds_bpermute_b32 v35, v56, v34
	s_waitcnt lgkmcnt(0)
	v_add_f32_e32 v34, v34, v35
	ds_bpermute_b32 v35, v57, v34
	s_waitcnt lgkmcnt(0)
	v_add_f32_e32 v34, v34, v35
	v_fmamk_f32 v34, v34, 0x3a000000, v214
	v_cmp_gt_f32_e32 vcc, s33, v34
	v_mul_f32_e32 v35, 0x4f800000, v34
	s_nop 0
	v_cndmask_b32_e32 v34, v34, v35, vcc
	v_sqrt_f32_e32 v35, v34
	s_nop 0
	v_add_u32_e32 v36, -1, v35
	v_fma_f32 v37, -v36, v35, v34
	v_cmp_ge_f32_e64 s[4:5], 0, v37
	v_add_u32_e32 v37, 1, v35
	s_nop 0
	v_cndmask_b32_e64 v36, v35, v36, s[4:5]
	v_fma_f32 v35, -v37, v35, v34
	v_cmp_lt_f32_e64 s[4:5], 0, v35
	s_nop 1
	v_cndmask_b32_e64 v35, v36, v37, s[4:5]
	v_mul_f32_e32 v36, 0x37800000, v35
	v_cndmask_b32_e32 v35, v35, v36, vcc
	v_cmp_class_f32_e32 vcc, v34, v215
	s_nop 1
	v_cndmask_b32_e32 v34, v35, v34, vcc
	v_div_scale_f32 v35, s[4:5], v34, v34, 1.0
	v_rcp_f32_e32 v36, v35
	s_nop 0
	v_fma_f32 v37, -v35, v36, 1.0
	v_fmac_f32_e32 v36, v37, v36
	v_div_scale_f32 v37, vcc, 1.0, v34, 1.0
	v_mul_f32_e32 v52, v37, v36
	v_fma_f32 v58, -v35, v52, v37
	v_fmac_f32_e32 v52, v58, v36
	v_fma_f32 v35, -v35, v52, v37
	v_div_fmas_f32 v35, v35, v36, v52
	v_div_fixup_f32 v52, v35, v34, 1.0
	v_pk_mul_f32 v[2:3], v[116:117], v[52:53] op_sel_hi:[1,0]
	v_pk_mul_f32 v[4:5], v[118:119], v[52:53] op_sel_hi:[1,0]
	v_pk_mul_f32 v[2:3], v[64:65], v[2:3]
	v_pk_mul_f32 v[4:5], v[66:67], v[4:5]
	v_cvt_pk_bf16_f32 v8, v2, v3
	v_cvt_pk_bf16_f32 v9, v4, v5
	global_store_dwordx2 v[48:49], v[8:9], off offset:-3584
	v_pk_mul_f32 v[2:3], v[120:121], v[52:53] op_sel_hi:[1,0]
	v_pk_mul_f32 v[4:5], v[122:123], v[52:53] op_sel_hi:[1,0]
	v_pk_mul_f32 v[2:3], v[68:69], v[2:3]
	v_pk_mul_f32 v[4:5], v[70:71], v[4:5]
	v_cvt_pk_bf16_f32 v10, v2, v3
	v_cvt_pk_bf16_f32 v11, v4, v5
	global_store_dwordx2 v[48:49], v[10:11], off offset:-3072
	v_pk_mul_f32 v[2:3], v[124:125], v[52:53] op_sel_hi:[1,0]
	v_pk_mul_f32 v[4:5], v[126:127], v[52:53] op_sel_hi:[1,0]
	v_pk_mul_f32 v[2:3], v[72:73], v[2:3]
	v_pk_mul_f32 v[4:5], v[74:75], v[4:5]
	v_cvt_pk_bf16_f32 v12, v2, v3
	v_cvt_pk_bf16_f32 v13, v4, v5
	global_store_dwordx2 v[48:49], v[12:13], off offset:-2560
	v_pk_mul_f32 v[2:3], v[128:129], v[52:53] op_sel_hi:[1,0]
	v_pk_mul_f32 v[4:5], v[130:131], v[52:53] op_sel_hi:[1,0]
	v_pk_mul_f32 v[2:3], v[76:77], v[2:3]
	v_pk_mul_f32 v[4:5], v[78:79], v[4:5]
	v_cvt_pk_bf16_f32 v14, v2, v3
	v_cvt_pk_bf16_f32 v15, v4, v5
	global_store_dwordx2 v[48:49], v[14:15], off offset:-2048
	v_pk_mul_f32 v[2:3], v[132:133], v[52:53] op_sel_hi:[1,0]
	v_pk_mul_f32 v[4:5], v[134:135], v[52:53] op_sel_hi:[1,0]
	v_pk_mul_f32 v[2:3], v[80:81], v[2:3]
	v_pk_mul_f32 v[4:5], v[82:83], v[4:5]
	v_cvt_pk_bf16_f32 v16, v2, v3
	v_cvt_pk_bf16_f32 v17, v4, v5
	global_store_dwordx2 v[48:49], v[16:17], off offset:-1536
	v_pk_mul_f32 v[2:3], v[136:137], v[52:53] op_sel_hi:[1,0]
	v_pk_mul_f32 v[4:5], v[138:139], v[52:53] op_sel_hi:[1,0]
	v_pk_mul_f32 v[2:3], v[84:85], v[2:3]
	v_pk_mul_f32 v[4:5], v[86:87], v[4:5]
	v_cvt_pk_bf16_f32 v18, v2, v3
	v_cvt_pk_bf16_f32 v19, v4, v5
	global_store_dwordx2 v[48:49], v[18:19], off offset:-1024
	v_pk_mul_f32 v[2:3], v[140:141], v[52:53] op_sel_hi:[1,0]
	v_pk_mul_f32 v[4:5], v[142:143], v[52:53] op_sel_hi:[1,0]
	v_pk_mul_f32 v[2:3], v[88:89], v[2:3]
	v_pk_mul_f32 v[4:5], v[90:91], v[4:5]
	v_cvt_pk_bf16_f32 v20, v2, v3
	v_cvt_pk_bf16_f32 v21, v4, v5
	global_store_dwordx2 v[48:49], v[20:21], off offset:-512
	v_pk_mul_f32 v[2:3], v[144:145], v[52:53] op_sel_hi:[1,0]
	v_pk_mul_f32 v[4:5], v[146:147], v[52:53] op_sel_hi:[1,0]
	v_pk_mul_f32 v[2:3], v[92:93], v[2:3]
	v_pk_mul_f32 v[4:5], v[94:95], v[4:5]
	v_cvt_pk_bf16_f32 v22, v2, v3
	v_cvt_pk_bf16_f32 v23, v4, v5
	global_store_dwordx2 v[48:49], v[22:23], off
	v_lshl_add_u64 v[48:49], v[48:49], 0, s[6:7]
	s_branch .LBB0_504
; __device__ __forceinline__ unsigned cvt_pk_bf16(float lo, float hi) { f32x2 v = {lo, hi}; bf16x2_t b = __builtin_convertvector(v, bf16x2_t); return __builtin_bit_cast(unsigned, b); }
; __device__ __forceinline__ void rms_row_to_bf16(const float* xrow, const float* g, bf16* orow, int lane) {
;     const f32x4* xr = (const f32x4*)xrow + lane; const f32x4* gr = (const f32x4*)g + lane;
;     f32x4 v[8]; float s = 0.f;
; #pragma unroll
;     for (int j = 0; j < 8; ++j) { v[j] = xr[64 * j]; s += (v[j].x * v[j].x + v[j].y * v[j].y) + (v[j].z * v[j].z + v[j].w * v[j].w); }
;     const float r = 1.0f / sqrtf(wave_sum(s) * (1.0f / DM) + EPS);
;     u32x2* o8 = (u32x2*)orow + lane;
; #pragma unroll
;     for (int j = 0; j < 8; ++j) { const f32x4 gg = gr[64 * j]; u32x2 w; w.x = cvt_pk_bf16(v[j].x * r * gg.x, v[j].y * r * gg.y); w.y = cvt_pk_bf16(v[j].z * r * gg.z, v[j].w * r * gg.w); o8[64 * j] = w; }
; }
.Lrms_last_b:
	s_waitcnt vmcnt(0)
	v_pk_mul_f32 v[4:5], v[148:149], v[148:149]
	v_pk_mul_f32 v[6:7], v[150:151], v[150:151]
	v_pk_fma_f32 v[4:5], v[152:153], v[152:153], v[4:5]
	v_pk_fma_f32 v[6:7], v[154:155], v[154:155], v[6:7]
	v_pk_fma_f32 v[4:5], v[156:157], v[156:157], v[4:5]
	v_pk_fma_f32 v[6:7], v[158:159], v[158:159], v[6:7]
	v_pk_fma_f32 v[4:5], v[160:161], v[160:161], v[4:5]
	v_pk_fma_f32 v[6:7], v[162:163], v[162:163], v[6:7]
	v_pk_fma_f32 v[4:5], v[164:165], v[164:165], v[4:5]
	v_pk_fma_f32 v[6:7], v[166:167], v[166:167], v[6:7]
	v_pk_fma_f32 v[4:5], v[168:169], v[168:169], v[4:5]
	v_pk_fma_f32 v[6:7], v[170:171], v[170:171], v[6:7]
	v_pk_fma_f32 v[4:5], v[172:173], v[172:173], v[4:5]
	v_pk_fma_f32 v[6:7], v[174:175], v[174:175], v[6:7]
	v_pk_fma_f32 v[4:5], v[176:177], v[176:177], v[4:5]
	v_pk_fma_f32 v[6:7], v[178:179], v[178:179], v[6:7]
	v_pk_add_f32 v[4:5], v[4:5], v[6:7]
	s_nop 0
	v_add_f32_e32 v34, v4, v5
	ds_bpermute_b32 v35, v1, v34
	s_waitcnt lgkmcnt(0)
	v_add_f32_e32 v34, v34, v35
	ds_bpermute_b32 v35, v53, v34
	s_waitcnt lgkmcnt(0)
	v_add_f32_e32 v34, v34, v35
	ds_bpermute_b32 v35, v54, v34
	s_waitcnt lgkmcnt(0)
	v_add_f32_e32 v34, v34, v35
	ds_bpermute_b32 v35, v55, v34
	s_waitcnt lgkmcnt(0)
	v_add_f32_e32 v34, v34, v35
	ds_bpermute_b32 v35, v56, v34
	s_waitcnt lgkmcnt(0)
	v_add_f32_e32 v34, v34, v35
	ds_bpermute_b32 v35, v57, v34
	s_waitcnt lgkmcnt(0)
	v_add_f32_e32 v34, v34, v35
	v_fmamk_f32 v34, v34, 0x3a000000, v214
	v_cmp_gt_f32_e32 vcc, s33, v34
	v_mul_f32_e32 v35, 0x4f800000, v34
	s_nop 0
	v_cndmask_b32_e32 v34, v34, v35, vcc
	v_sqrt_f32_e32 v35, v34
	s_nop 0
	v_add_u32_e32 v36, -1, v35
	v_fma_f32 v37, -v36, v35, v34
	v_cmp_ge_f32_e64 s[4:5], 0, v37
	v_add_u32_e32 v37, 1, v35
	s_nop 0
	v_cndmask_b32_e64 v36, v35, v36, s[4:5]
	v_fma_f32 v35, -v37, v35, v34
	v_cmp_lt_f32_e64 s[4:5], 0, v35
	s_nop 1
	v_cndmask_b32_e64 v35, v36, v37, s[4:5]
	v_mul_f32_e32 v36, 0x37800000, v35
	v_cndmask_b32_e32 v35, v35, v36, vcc
	v_cmp_class_f32_e32 vcc, v34, v215
	s_nop 1
	v_cndmask_b32_e32 v34, v35, v34, vcc
	v_div_scale_f32 v35, s[4:5], v34, v34, 1.0
	v_rcp_f32_e32 v36, v35
	s_nop 0
	v_fma_f32 v37, -v35, v36, 1.0
	v_fmac_f32_e32 v36, v37, v36
	v_div_scale_f32 v37, vcc, 1.0, v34, 1.0
	v_mul_f32_e32 v52, v37, v36
	v_fma_f32 v58, -v35, v52, v37
	v_fmac_f32_e32 v52, v58, v36
	v_fma_f32 v35, -v35, v52, v37
	v_div_fmas_f32 v35, v35, v36, v52
	v_div_fixup_f32 v52, v35, v34, 1.0
	v_pk_mul_f32 v[2:3], v[148:149], v[52:53] op_sel_hi:[1,0]
	v_pk_mul_f32 v[4:5], v[150:151], v[52:53] op_sel_hi:[1,0]
	v_pk_mul_f32 v[2:3], v[64:65], v[2:3]
	v_pk_mul_f32 v[4:5], v[66:67], v[4:5]
	v_cvt_pk_bf16_f32 v8, v2, v3
	v_cvt_pk_bf16_f32 v9, v4, v5
	global_store_dwordx2 v[48:49], v[8:9], off offset:-3584
	v_pk_mul_f32 v[2:3], v[152:153], v[52:53] op_sel_hi:[1,0]
	v_pk_mul_f32 v[4:5], v[154:155], v[52:53] op_sel_hi:[1,0]
	v_pk_mul_f32 v[2:3], v[68:69], v[2:3]
	v_pk_mul_f32 v[4:5], v[70:71], v[4:5]
	v_cvt_pk_bf16_f32 v10, v2, v3
	v_cvt_pk_bf16_f32 v11, v4, v5
	global_store_dwordx2 v[48:49], v[10:11], off offset:-3072
	v_pk_mul_f32 v[2:3], v[156:157], v[52:53] op_sel_hi:[1,0]
	v_pk_mul_f32 v[4:5], v[158:159], v[52:53] op_sel_hi:[1,0]
	v_pk_mul_f32 v[2:3], v[72:73], v[2:3]
	v_pk_mul_f32 v[4:5], v[74:75], v[4:5]
	v_cvt_pk_bf16_f32 v12, v2, v3
	v_cvt_pk_bf16_f32 v13, v4, v5
	global_store_dwordx2 v[48:49], v[12:13], off offset:-2560
	v_pk_mul_f32 v[2:3], v[160:161], v[52:53] op_sel_hi:[1,0]
	v_pk_mul_f32 v[4:5], v[162:163], v[52:53] op_sel_hi:[1,0]
	v_pk_mul_f32 v[2:3], v[76:77], v[2:3]
	v_pk_mul_f32 v[4:5], v[78:79], v[4:5]
	v_cvt_pk_bf16_f32 v14, v2, v3
	v_cvt_pk_bf16_f32 v15, v4, v5
	global_store_dwordx2 v[48:49], v[14:15], off offset:-2048
	v_pk_mul_f32 v[2:3], v[164:165], v[52:53] op_sel_hi:[1,0]
	v_pk_mul_f32 v[4:5], v[166:167], v[52:53] op_sel_hi:[1,0]
	v_pk_mul_f32 v[2:3], v[80:81], v[2:3]
	v_pk_mul_f32 v[4:5], v[82:83], v[4:5]
	v_cvt_pk_bf16_f32 v16, v2, v3
	v_cvt_pk_bf16_f32 v17, v4, v5
	global_store_dwordx2 v[48:49], v[16:17], off offset:-1536
	v_pk_mul_f32 v[2:3], v[168:169], v[52:53] op_sel_hi:[1,0]
	v_pk_mul_f32 v[4:5], v[170:171], v[52:53] op_sel_hi:[1,0]
	v_pk_mul_f32 v[2:3], v[84:85], v[2:3]
	v_pk_mul_f32 v[4:5], v[86:87], v[4:5]
	v_cvt_pk_bf16_f32 v18, v2, v3
	v_cvt_pk_bf16_f32 v19, v4, v5
	global_store_dwordx2 v[48:49], v[18:19], off offset:-1024
	v_pk_mul_f32 v[2:3], v[172:173], v[52:53] op_sel_hi:[1,0]
	v_pk_mul_f32 v[4:5], v[174:175], v[52:53] op_sel_hi:[1,0]
	v_pk_mul_f32 v[2:3], v[88:89], v[2:3]
	v_pk_mul_f32 v[4:5], v[90:91], v[4:5]
	v_cvt_pk_bf16_f32 v20, v2, v3
	v_cvt_pk_bf16_f32 v21, v4, v5
	global_store_dwordx2 v[48:49], v[20:21], off offset:-512
	v_pk_mul_f32 v[2:3], v[176:177], v[52:53] op_sel_hi:[1,0]
	v_pk_mul_f32 v[4:5], v[178:179], v[52:53] op_sel_hi:[1,0]
	v_pk_mul_f32 v[2:3], v[92:93], v[2:3]
	v_pk_mul_f32 v[4:5], v[94:95], v[4:5]
	v_cvt_pk_bf16_f32 v22, v2, v3
	v_cvt_pk_bf16_f32 v23, v4, v5
	global_store_dwordx2 v[48:49], v[22:23], off
	v_lshl_add_u64 v[48:49], v[48:49], 0, s[6:7]
